# v12 + code placement: 12 bytes of padding so the last out-projection K-loop head sits at its hipcc byte phase (0 mod 64)
# speedup vs baseline: 1.0023x; 1.0023x over previous
; __global__ void __launch_bounds__(NTHR) mega(Params p) {
;     ...
;     if (IN(7)) {
;         const bool split = (gridDim.x == 256);
;         pg8::Gemm g{(const bf16_t*)(ws + WS_Y2), (const bf16_t*)(ws + WS_WOUTO), T, 1024, 1536, 1536};
;         pg8::StaticOrder S; S.init(T, 1024, gridDim.x, blockIdx.x, split ? 512 : -1);
;         EpiOutResB E{(bf16_t*)(ws + WS_XB), (float*)(ws + WS_RSQ2)};
;         pg8::gemm_phase<EpiOutResB, pg8::StaticOrder>(L, g, S, E);
.LBB0_1401:
	s_cmp_lt_i32 s46, 8
	s_cselect_b64 s[4:5], -1, 0
	s_and_b64 s[8:9], s[4:5], s[0:1]
	s_andn2_b64 vcc, exec, s[8:9]
	s_cbranch_vccnz .LBB0_1505
	s_nop 0
	s_nop 0
	s_nop 0
